# up-GEMM k-loop: loop-edge rotation (loop control + next-iteration pointer selects moved into phase-4 LDS-latency shadow), loop-invariant LDS read base with immediate offsets, per-phase scalar setup do
# speedup vs baseline: 1.0055x; 1.0055x over previous
;     __host__ __device__ bool next(int i, Unit& u) const { if (!StaticOrder::next(i, u)) return false; u.pm = nM - 1 - u.pm; return true; }
; #define PG8_STAGE(bufoff, gbase, voff) do { _Pragma("unroll") for (int _i = 0; _i < 2; ++_i) \
;         __builtin_amdgcn_global_load_lds((const unsigned*)((const char*)(gbase) + (voff)[_i]), (LAS unsigned*)(lds + (bufoff) + ldsw + _i * 8192), 16, 0, 0); } while (0)
; #define PG8_LDA(dst, b, h) do { _Pragma("unroll") for (int m = 0; m < 4; ++m) _Pragma("unroll") for (int k = 0; k < 2; ++k) dst[m][k] = *(const LAS bf16x8*)(lds + PG8_SA(b, h) + aoff + m * 2048 + k * 1024); } while (0)
; #define PG8_LDB(dst, b, h) do { _Pragma("unroll") for (int n = 0; n < 2; ++n) _Pragma("unroll") for (int k = 0; k < 2; ++k) dst[n][k] = *(const LAS bf16x8*)(lds + PG8_SB(b, h) + boff + n * 2048 + k * 1024); } while (0)
; #define PG8_SCHED __builtin_amdgcn_sched_barrier(0)
; template <class Epi, class Sched, bool ALIGN_EPI = false, bool SP2 = false>
; __device__ __forceinline__ void gemm_phase(LAS unsigned char* lds, const Gemm g, const Sched& S, const Epi& E, int wid) {
;     ...
;         const bool has_next = S.next(ui + 1, nxt);
;         const char* nA = has_next ? (const char*)g.A + (size_t)nxt.pm * tstepA + (size_t)nxt.pn * g.a_pn_off : cA; const char* nB = has_next ? (const char*)g.Bt + (size_t)nxt.pn * tstepB : cB;
; #pragma nounroll
;         for (int t = 0; t < nt; t += 2) {
;             const bool last = (t == nt - 2);
;             const char* a1 = cA + (size_t)(t + 1) * kstep;
;             const char* a2 = last ? nA : cA + (size_t)(t + 2) * kstep; const char* b2 = last ? nB : cB + (size_t)(t + 2) * kstep;
;             const char* a3 = a2 + kstep; const char* b3 = b2 + kstep;
;             if constexpr (SP2) {
;             PG8_LDB(B0, 0, 0); PG8_LDB(B1, 0, 1); PG8_SCHED; PG8_LDA(At, 0, 0); PG8_STAGE(PG8_SA(1, 1), a1 + hstepA, voffA);
;     ...
; #pragma unroll
;         for (int a = 0; a < 2; ++a)
; #pragma unroll
;             for (int b = 0; b < 2; ++b)
; #pragma unroll
;                 for (int m = 0; m < 4; ++m)
; #pragma unroll
;                     for (int n = 0; n < 2; ++n) acc[a][b][m][n] = (f32x4){0.f, 0.f, 0.f, 0.f};
;         cur = nxt; cA = nA; cB = nB; ++ui;
.LBB0_967:
	s_ashr_i32 s41, s40, 31
	s_lshl_b64 s[42:43], s[40:41], 20
	s_add_u32 s50, s97, s42
	s_addc_u32 s51, s27, s43
	s_and_b64 s[42:43], s[10:11], exec
	s_cselect_b32 s41, s51, s55
	s_cselect_b32 s42, s50, s54
	s_ashr_i32 s93, s92, 31
	s_lshl_b64 s[48:49], s[92:93], 20
	s_add_u32 s52, s6, s48
	s_addc_u32 s53, s7, s49
	s_and_b64 s[48:49], s[10:11], exec
	s_cselect_b32 s43, s53, s57
	s_cselect_b32 s59, s52, s56
	s_add_u32 s60, s56, 0x100
	v_mov_b32_e32 v8, 0
	s_addc_u32 s61, s57, 0
	s_mov_b32 s93, -2
	v_mov_b32_e32 v9, v8
	v_mov_b32_e32 v10, v8
	v_mov_b32_e32 v11, v8
	v_mov_b32_e32 v64, v8
	v_mov_b32_e32 v65, v8
	v_mov_b32_e32 v66, v8
	v_mov_b32_e32 v67, v8
	v_mov_b32_e32 v12, v8
	v_mov_b32_e32 v13, v8
	v_mov_b32_e32 v14, v8
	v_mov_b32_e32 v15, v8
	v_mov_b32_e32 v68, v8
	v_mov_b32_e32 v69, v8
	v_mov_b32_e32 v70, v8
	v_mov_b32_e32 v71, v8
	v_mov_b32_e32 v0, v8
	v_mov_b32_e32 v1, v8
	v_mov_b32_e32 v2, v8
	v_mov_b32_e32 v3, v8
	v_mov_b32_e32 v76, v8
	v_mov_b32_e32 v77, v8
	v_mov_b32_e32 v78, v8
	v_mov_b32_e32 v79, v8
	v_mov_b32_e32 v20, v8
	v_mov_b32_e32 v21, v8
	v_mov_b32_e32 v22, v8
	v_mov_b32_e32 v23, v8
	v_mov_b32_e32 v84, v8
	v_mov_b32_e32 v85, v8
	v_mov_b32_e32 v86, v8
	v_mov_b32_e32 v87, v8
	v_mov_b32_e32 v16, v8
	v_mov_b32_e32 v17, v8
	v_mov_b32_e32 v18, v8
	v_mov_b32_e32 v19, v8
	v_mov_b32_e32 v72, v8
	v_mov_b32_e32 v73, v8
	v_mov_b32_e32 v74, v8
	v_mov_b32_e32 v75, v8
	v_mov_b32_e32 v24, v8
	v_mov_b32_e32 v25, v8
	v_mov_b32_e32 v26, v8
	v_mov_b32_e32 v27, v8
	v_mov_b32_e32 v80, v8
	v_mov_b32_e32 v81, v8
	v_mov_b32_e32 v82, v8
	v_mov_b32_e32 v83, v8
	v_mov_b32_e32 v4, v8
	v_mov_b32_e32 v5, v8
	v_mov_b32_e32 v6, v8
	v_mov_b32_e32 v7, v8
	v_mov_b32_e32 v88, v8
	v_mov_b32_e32 v89, v8
	v_mov_b32_e32 v90, v8
	v_mov_b32_e32 v91, v8
	v_mov_b32_e32 v28, v8
	v_mov_b32_e32 v29, v8
	v_mov_b32_e32 v30, v8
	v_mov_b32_e32 v31, v8
	v_mov_b32_e32 v92, v8
	v_mov_b32_e32 v93, v8
	v_mov_b32_e32 v94, v8
	v_mov_b32_e32 v95, v8
	v_mov_b32_e32 v40, v8
	v_mov_b32_e32 v41, v8
	v_mov_b32_e32 v42, v8
	v_mov_b32_e32 v43, v8
	v_mov_b32_e32 v96, v8
	v_mov_b32_e32 v97, v8
	v_mov_b32_e32 v98, v8
	v_mov_b32_e32 v99, v8
	v_mov_b32_e32 v44, v8
	v_mov_b32_e32 v45, v8
	v_mov_b32_e32 v46, v8
	v_mov_b32_e32 v47, v8
	s_waitcnt vmcnt(0)
	v_mov_b32_e32 v136, v8
	v_mov_b32_e32 v137, v8
	v_mov_b32_e32 v138, v8
	v_mov_b32_e32 v139, v8
	v_mov_b32_e32 v32, v8
	v_mov_b32_e32 v33, v8
	v_mov_b32_e32 v34, v8
	v_mov_b32_e32 v35, v8
	v_mov_b32_e32 v148, v8
	v_mov_b32_e32 v149, v8
	v_mov_b32_e32 v150, v8
	v_mov_b32_e32 v151, v8
	v_mov_b32_e32 v52, v8
	v_mov_b32_e32 v53, v8
	v_mov_b32_e32 v54, v8
	v_mov_b32_e32 v55, v8
	v_mov_b32_e32 v156, v8
	v_mov_b32_e32 v157, v8
	v_mov_b32_e32 v158, v8
	v_mov_b32_e32 v159, v8
	v_mov_b32_e32 v48, v8
	v_mov_b32_e32 v49, v8
	v_mov_b32_e32 v50, v8
	v_mov_b32_e32 v51, v8
	v_mov_b32_e32 v100, v8
	v_mov_b32_e32 v101, v8
	v_mov_b32_e32 v102, v8
	v_mov_b32_e32 v103, v8
	v_mov_b32_e32 v56, v8
	v_mov_b32_e32 v57, v8
	v_mov_b32_e32 v58, v8
	v_mov_b32_e32 v59, v8
	v_mov_b32_e32 v140, v8
	v_mov_b32_e32 v141, v8
	v_mov_b32_e32 v142, v8
	v_mov_b32_e32 v143, v8
	v_mov_b32_e32 v36, v8
	v_mov_b32_e32 v37, v8
	v_mov_b32_e32 v38, v8
	v_mov_b32_e32 v39, v8
	v_mov_b32_e32 v152, v8
	v_mov_b32_e32 v153, v8
	v_mov_b32_e32 v154, v8
	v_mov_b32_e32 v155, v8
	v_mov_b32_e32 v60, v8
	v_mov_b32_e32 v61, v8
	v_mov_b32_e32 v62, v8
	v_mov_b32_e32 v63, v8
	v_mov_b32_e32 v160, v8
	v_mov_b32_e32 v161, v8
	v_mov_b32_e32 v162, v8
	v_mov_b32_e32 v163, v8
	s_add_u32 s48, s54, 0x100
	s_addc_u32 s49, s55, 0
	s_mov_b64 vcc, s[60:61]
	s_mov_b32 m0, s94
	s_add_u32 s100, s54, 0x80
	s_addc_u32 s101, s55, 0
	v_add_u32_e32 v236, 0x10000, v228
.LBB0_968:
	global_load_lds_dwordx4 v176, s[100:101]
	s_mov_b32 m0, s95
	ds_read_b128 v[104:107], v236
	ds_read_b128 v[108:111], v236 offset:1024
	ds_read_b128 v[112:115], v236 offset:2048
	ds_read_b128 v[116:119], v236 offset:3072
	global_load_lds_dwordx4 v174, s[100:101]
	s_add_i32 m0, s79, 0xc000
	s_add_u32 s100, s100, 0x80000
	s_addc_u32 s101, s101, 0
	ds_read_b128 v[120:123], v236 offset:16384
	ds_read_b128 v[124:127], v236 offset:17408
	ds_read_b128 v[128:131], v236 offset:18432
	ds_read_b128 v[132:135], v236 offset:19456
	global_load_lds_dwordx4 v176, s[100:101]
	s_add_i32 m0, s79, 0xe000
	ds_read_b128 v[144:147], v231
	ds_read_b128 v[164:167], v231 offset:1024
	ds_read_b128 v[168:171], v231 offset:2048
	ds_read_b128 v[186:189], v231 offset:3072
	global_load_lds_dwordx4 v174, s[100:101]
	ds_read_b128 v[200:203], v231 offset:4096
	ds_read_b128 v[204:207], v231 offset:5120
	ds_read_b128 v[208:211], v231 offset:6144
	ds_read_b128 v[212:215], v231 offset:7168
	s_mov_b64 s[100:101], vcc
	s_add_u32 s62, vcc_lo, 0x80000
	s_addc_u32 s63, vcc_hi, 0
	s_add_i32 m0, s89, 0x10000
	s_waitcnt vmcnt(8) lgkmcnt(0)
	s_barrier
; #define PG8_STAGE(bufoff, gbase, voff) do { _Pragma("unroll") for (int _i = 0; _i < 2; ++_i) \
;         __builtin_amdgcn_global_load_lds((const unsigned*)((const char*)(gbase) + (voff)[_i]), (LAS unsigned*)(lds + (bufoff) + ldsw + _i * 8192), 16, 0, 0); } while (0)
; #define PG8_LDA(dst, b, h) do { _Pragma("unroll") for (int m = 0; m < 4; ++m) _Pragma("unroll") for (int k = 0; k < 2; ++k) dst[m][k] = *(const LAS bf16x8*)(lds + PG8_SA(b, h) + aoff + m * 2048 + k * 1024); } while (0)
; #define PG8_LDB(dst, b, h) do { _Pragma("unroll") for (int n = 0; n < 2; ++n) _Pragma("unroll") for (int k = 0; k < 2; ++k) dst[n][k] = *(const LAS bf16x8*)(lds + PG8_SB(b, h) + boff + n * 2048 + k * 1024); } while (0)
; #define PG8_MMA(ai, bj, At, Bt) do { __builtin_amdgcn_s_setprio(1); _Pragma("unroll") for (int m = 0; m < 4; ++m) _Pragma("unroll") for (int n = 0; n < 2; ++n) _Pragma("unroll") for (int k = 0; k < 2; ++k) \
;         acc[ai][bj][m][n] = __builtin_amdgcn_mfma_f32_16x16x32_bf16(Bt[n][k], At[m][k], acc[ai][bj][m][n], 0, 0, 0); __builtin_amdgcn_s_setprio(0); } while (0)
; #define PG8_WAIT_V(n) asm volatile("s_waitcnt vmcnt(" #n ")" ::: "memory")
; #define PG8_WAIT_L(n) asm volatile("s_waitcnt lgkmcnt(" #n ")" ::: "memory")
; #define PG8_BAR __builtin_amdgcn_s_barrier()
; #define PG8_SCHED __builtin_amdgcn_sched_barrier(0)
; template <class Epi, class Sched, bool ALIGN_EPI = false, bool SP2 = false>
; __device__ __forceinline__ void gemm_phase(LAS unsigned char* lds, const Gemm g, const Sched& S, const Epi& E, int wid) {
;     ...
;             PG8_LDB(B0, 0, 0); PG8_LDB(B1, 0, 1); PG8_SCHED; PG8_LDA(At, 0, 0); PG8_STAGE(PG8_SA(1, 1), a1 + hstepA, voffA);
;             PG8_WAIT_V(8); PG8_WAIT_L(0); PG8_BAR; PG8_MMA(0, 0, At, B0); PG8_MMA(0, 1, At, B1); PG8_BAR; PG8_SCHED;
;             PG8_LDA(At, 0, 1); PG8_STAGE(PG8_SB(0, 0), b2, voffB); PG8_STAGE(PG8_SB(0, 1), b2 + hstepB, voffB); PG8_STAGE(PG8_SA(0, 0), a2, voffA);
;             PG8_WAIT_V(8); PG8_WAIT_L(0); PG8_BAR; PG8_MMA(1, 0, At, B0); PG8_MMA(1, 1, At, B1); PG8_BAR; PG8_SCHED;
;             PG8_LDB(B0, 1, 0); PG8_LDB(B1, 1, 1); PG8_SCHED; PG8_LDA(At, 1, 0); PG8_STAGE(PG8_SA(0, 1), a2 + hstepA, voffA);
	s_setprio 1
	v_mfma_f32_16x16x32_bf16 v[160:163], v[104:107], v[144:147], v[160:163]
	v_mfma_f32_16x16x32_bf16 v[60:63], v[112:115], v[144:147], v[60:63]
	v_mfma_f32_16x16x32_bf16 v[152:155], v[104:107], v[168:171], v[152:155]
	v_mfma_f32_16x16x32_bf16 v[36:39], v[112:115], v[168:171], v[36:39]
	v_mfma_f32_16x16x32_bf16 v[140:143], v[104:107], v[200:203], v[140:143]
	v_mfma_f32_16x16x32_bf16 v[56:59], v[112:115], v[200:203], v[56:59]
	v_mfma_f32_16x16x32_bf16 v[100:103], v[104:107], v[208:211], v[100:103]
	v_mfma_f32_16x16x32_bf16 v[48:51], v[112:115], v[208:211], v[48:51]
	v_mfma_f32_16x16x32_bf16 v[160:163], v[108:111], v[164:167], v[160:163]
	v_mfma_f32_16x16x32_bf16 v[60:63], v[116:119], v[164:167], v[60:63]
	v_mfma_f32_16x16x32_bf16 v[152:155], v[108:111], v[186:189], v[152:155]
	v_mfma_f32_16x16x32_bf16 v[36:39], v[116:119], v[186:189], v[36:39]
	v_mfma_f32_16x16x32_bf16 v[140:143], v[108:111], v[204:207], v[140:143]
	v_mfma_f32_16x16x32_bf16 v[56:59], v[116:119], v[204:207], v[56:59]
	v_mfma_f32_16x16x32_bf16 v[100:103], v[108:111], v[212:215], v[100:103]
	v_mfma_f32_16x16x32_bf16 v[48:51], v[116:119], v[212:215], v[48:51]
	s_setprio 0
	s_setprio 1
	v_mfma_f32_16x16x32_bf16 v[156:159], v[120:123], v[144:147], v[156:159]
	v_mfma_f32_16x16x32_bf16 v[52:55], v[128:131], v[144:147], v[52:55]
	v_mfma_f32_16x16x32_bf16 v[32:35], v[128:131], v[168:171], v[32:35]
	v_mfma_f32_16x16x32_bf16 v[136:139], v[120:123], v[200:203], v[136:139]
	v_mfma_f32_16x16x32_bf16 v[44:47], v[128:131], v[200:203], v[44:47]
	v_mfma_f32_16x16x32_bf16 v[96:99], v[120:123], v[208:211], v[96:99]
	v_mfma_f32_16x16x32_bf16 v[40:43], v[128:131], v[208:211], v[40:43]
	v_mfma_f32_16x16x32_bf16 v[156:159], v[124:127], v[164:167], v[156:159]
	v_mfma_f32_16x16x32_bf16 v[52:55], v[132:135], v[164:167], v[52:55]
	v_mfma_f32_16x16x32_bf16 v[144:147], v[120:123], v[168:171], v[148:151]
	v_mfma_f32_16x16x32_bf16 v[32:35], v[132:135], v[186:189], v[32:35]
	v_mfma_f32_16x16x32_bf16 v[136:139], v[124:127], v[204:207], v[136:139]
	v_mfma_f32_16x16x32_bf16 v[44:47], v[132:135], v[204:207], v[44:47]
	v_mfma_f32_16x16x32_bf16 v[96:99], v[124:127], v[212:215], v[96:99]
	v_mfma_f32_16x16x32_bf16 v[40:43], v[132:135], v[212:215], v[40:43]
	v_mfma_f32_16x16x32_bf16 v[144:147], v[124:127], v[186:189], v[144:147]
	s_setprio 0
	s_barrier
	global_load_lds_dwordx4 v192, s[100:101]
	s_add_i32 m0, s89, 0x12000
	ds_read_b128 v[148:151], v231 offset:16384
	ds_read_b128 v[164:167], v231 offset:17408
	global_load_lds_dwordx4 v172, s[100:101]
	s_add_i32 m0, s89, 0x14000
	ds_read_b128 v[168:171], v231 offset:18432
	ds_read_b128 v[186:189], v231 offset:19456
	global_load_lds_dwordx4 v192, s[62:63]
	s_add_i32 m0, s89, 0x16000
	ds_read_b128 v[200:203], v231 offset:20480
	ds_read_b128 v[204:207], v231 offset:21504
	global_load_lds_dwordx4 v172, s[62:63]
	ds_read_b128 v[208:211], v231 offset:22528
	ds_read_b128 v[212:215], v231 offset:23552
	s_add_u32 s62, s48, 0x80000
	s_addc_u32 s63, s49, 0
	s_mov_b32 m0, s79
	s_waitcnt vmcnt(6) lgkmcnt(0)
	s_barrier
	s_setprio 1
	v_mfma_f32_16x16x32_bf16 v[92:95], v[104:107], v[148:151], v[92:95]
	v_mfma_f32_16x16x32_bf16 v[28:31], v[112:115], v[148:151], v[28:31]
	v_mfma_f32_16x16x32_bf16 v[88:91], v[104:107], v[168:171], v[88:91]
	v_mfma_f32_16x16x32_bf16 v[4:7], v[112:115], v[168:171], v[4:7]
	v_mfma_f32_16x16x32_bf16 v[80:83], v[104:107], v[200:203], v[80:83]
	v_mfma_f32_16x16x32_bf16 v[24:27], v[112:115], v[200:203], v[24:27]
	v_mfma_f32_16x16x32_bf16 v[72:75], v[104:107], v[208:211], v[72:75]
	v_mfma_f32_16x16x32_bf16 v[16:19], v[112:115], v[208:211], v[16:19]
	v_mfma_f32_16x16x32_bf16 v[92:95], v[108:111], v[164:167], v[92:95]
	v_mfma_f32_16x16x32_bf16 v[28:31], v[116:119], v[164:167], v[28:31]
	v_mfma_f32_16x16x32_bf16 v[88:91], v[108:111], v[186:189], v[88:91]
	v_mfma_f32_16x16x32_bf16 v[4:7], v[116:119], v[186:189], v[4:7]
	v_mfma_f32_16x16x32_bf16 v[80:83], v[108:111], v[204:207], v[80:83]
	v_mfma_f32_16x16x32_bf16 v[24:27], v[116:119], v[204:207], v[24:27]
	v_mfma_f32_16x16x32_bf16 v[72:75], v[108:111], v[212:215], v[72:75]
	v_mfma_f32_16x16x32_bf16 v[16:19], v[116:119], v[212:215], v[16:19]
	s_setprio 0
	s_setprio 1
	v_mfma_f32_16x16x32_bf16 v[84:87], v[120:123], v[148:151], v[84:87]
	v_mfma_f32_16x16x32_bf16 v[20:23], v[128:131], v[148:151], v[20:23]
	v_mfma_f32_16x16x32_bf16 v[76:79], v[120:123], v[168:171], v[76:79]
	v_mfma_f32_16x16x32_bf16 v[0:3], v[128:131], v[168:171], v[0:3]
	v_mfma_f32_16x16x32_bf16 v[68:71], v[120:123], v[200:203], v[68:71]
	v_mfma_f32_16x16x32_bf16 v[12:15], v[128:131], v[200:203], v[12:15]
	v_mfma_f32_16x16x32_bf16 v[64:67], v[120:123], v[208:211], v[64:67]
	v_mfma_f32_16x16x32_bf16 v[8:11], v[128:131], v[208:211], v[8:11]
	v_mfma_f32_16x16x32_bf16 v[84:87], v[124:127], v[164:167], v[84:87]
	v_mfma_f32_16x16x32_bf16 v[20:23], v[132:135], v[164:167], v[20:23]
	v_mfma_f32_16x16x32_bf16 v[76:79], v[124:127], v[186:189], v[76:79]
	v_mfma_f32_16x16x32_bf16 v[0:3], v[132:135], v[186:189], v[0:3]
	v_mfma_f32_16x16x32_bf16 v[68:71], v[124:127], v[204:207], v[68:71]
	v_mfma_f32_16x16x32_bf16 v[12:15], v[132:135], v[204:207], v[12:15]
	v_mfma_f32_16x16x32_bf16 v[64:67], v[124:127], v[212:215], v[64:67]
	v_mfma_f32_16x16x32_bf16 v[8:11], v[132:135], v[212:215], v[8:11]
	s_setprio 0
	s_barrier
; #define PG8_STAGE(bufoff, gbase, voff) do { _Pragma("unroll") for (int _i = 0; _i < 2; ++_i) \
;         __builtin_amdgcn_global_load_lds((const unsigned*)((const char*)(gbase) + (voff)[_i]), (LAS unsigned*)(lds + (bufoff) + ldsw + _i * 8192), 16, 0, 0); } while (0)
; #define PG8_LDA(dst, b, h) do { _Pragma("unroll") for (int m = 0; m < 4; ++m) _Pragma("unroll") for (int k = 0; k < 2; ++k) dst[m][k] = *(const LAS bf16x8*)(lds + PG8_SA(b, h) + aoff + m * 2048 + k * 1024); } while (0)
; #define PG8_LDB(dst, b, h) do { _Pragma("unroll") for (int n = 0; n < 2; ++n) _Pragma("unroll") for (int k = 0; k < 2; ++k) dst[n][k] = *(const LAS bf16x8*)(lds + PG8_SB(b, h) + boff + n * 2048 + k * 1024); } while (0)
; #define PG8_MMA(ai, bj, At, Bt) do { __builtin_amdgcn_s_setprio(1); _Pragma("unroll") for (int m = 0; m < 4; ++m) _Pragma("unroll") for (int n = 0; n < 2; ++n) _Pragma("unroll") for (int k = 0; k < 2; ++k) \
;         acc[ai][bj][m][n] = __builtin_amdgcn_mfma_f32_16x16x32_bf16(Bt[n][k], At[m][k], acc[ai][bj][m][n], 0, 0, 0); __builtin_amdgcn_s_setprio(0); } while (0)
; #define PG8_WAIT_V(n) asm volatile("s_waitcnt vmcnt(" #n ")" ::: "memory")
; #define PG8_WAIT_L(n) asm volatile("s_waitcnt lgkmcnt(" #n ")" ::: "memory")
; #define PG8_BAR __builtin_amdgcn_s_barrier()
; #define PG8_SCHED __builtin_amdgcn_sched_barrier(0)
; template <class Epi, class Sched, bool ALIGN_EPI = false, bool SP2 = false>
; __device__ __forceinline__ void gemm_phase(LAS unsigned char* lds, const Gemm g, const Sched& S, const Epi& E, int wid) {
;     ...
;         for (int t = 0; t < nt; t += 2) {
;             const bool last = (t == nt - 2);
;             const char* a1 = cA + (size_t)(t + 1) * kstep;
;             const char* a2 = last ? nA : cA + (size_t)(t + 2) * kstep; const char* b2 = last ? nB : cB + (size_t)(t + 2) * kstep;
;     ...
;             PG8_LDB(B0, 1, 0); PG8_LDB(B1, 1, 1); PG8_SCHED; PG8_LDA(At, 1, 0); PG8_STAGE(PG8_SA(0, 1), a2 + hstepA, voffA);
;             PG8_WAIT_V(8); PG8_WAIT_L(0); PG8_BAR; PG8_MMA(0, 0, At, B0); PG8_MMA(0, 1, At, B1); PG8_BAR; PG8_SCHED;
;             PG8_LDA(At, 1, 1); PG8_STAGE(PG8_SB(1, 0), b3, voffB); PG8_STAGE(PG8_SB(1, 1), b3 + hstepB, voffB); PG8_STAGE(PG8_SA(1, 0), a3, voffA);
;             PG8_WAIT_V(8); PG8_WAIT_L(0); PG8_BAR; PG8_MMA(1, 0, At, B0); PG8_MMA(1, 1, At, B1); PG8_BAR; PG8_SCHED;
	global_load_lds_dwordx4 v176, s[48:49]
	s_mov_b32 m0, s81
	ds_read_b128 v[104:107], v236 offset:32768
	ds_read_b128 v[108:111], v236 offset:33792
	ds_read_b128 v[112:115], v236 offset:34816
	ds_read_b128 v[116:119], v236 offset:35840
	global_load_lds_dwordx4 v174, s[48:49]
	s_mov_b32 m0, s77
	ds_read_b128 v[120:123], v236 offset:49152
	ds_read_b128 v[124:127], v236 offset:50176
	ds_read_b128 v[128:131], v236 offset:51200
	ds_read_b128 v[132:135], v236 offset:52224
	global_load_lds_dwordx4 v176, s[62:63]
	s_mov_b32 m0, s4
	ds_read_b128 v[148:151], v231 offset:32768
	ds_read_b128 v[164:167], v231 offset:33792
	ds_read_b128 v[168:171], v231 offset:34816
	ds_read_b128 v[186:189], v231 offset:35840
	global_load_lds_dwordx4 v174, s[62:63]
	ds_read_b128 v[200:203], v231 offset:36864
	ds_read_b128 v[204:207], v231 offset:37888
	ds_read_b128 v[208:211], v231 offset:38912
	ds_read_b128 v[212:215], v231 offset:39936
	s_add_u32 s100, vcc_lo, 0x80
	s_addc_u32 s101, vcc_hi, 0
	s_add_u32 s62, vcc_lo, 0x80080
	s_addc_u32 s63, vcc_hi, 0
	s_add_i32 m0, s89, 0x18000
	s_waitcnt vmcnt(8) lgkmcnt(0)
	s_barrier
	s_setprio 1
	v_mfma_f32_16x16x32_bf16 v[160:163], v[104:107], v[148:151], v[160:163]
	v_mfma_f32_16x16x32_bf16 v[60:63], v[112:115], v[148:151], v[60:63]
	v_mfma_f32_16x16x32_bf16 v[152:155], v[104:107], v[168:171], v[152:155]
	v_mfma_f32_16x16x32_bf16 v[36:39], v[112:115], v[168:171], v[36:39]
	v_mfma_f32_16x16x32_bf16 v[140:143], v[104:107], v[200:203], v[140:143]
	v_mfma_f32_16x16x32_bf16 v[56:59], v[112:115], v[200:203], v[56:59]
	v_mfma_f32_16x16x32_bf16 v[100:103], v[104:107], v[208:211], v[100:103]
	v_mfma_f32_16x16x32_bf16 v[48:51], v[112:115], v[208:211], v[48:51]
	v_mfma_f32_16x16x32_bf16 v[160:163], v[108:111], v[164:167], v[160:163]
	v_mfma_f32_16x16x32_bf16 v[60:63], v[116:119], v[164:167], v[60:63]
	v_mfma_f32_16x16x32_bf16 v[152:155], v[108:111], v[186:189], v[152:155]
	v_mfma_f32_16x16x32_bf16 v[36:39], v[116:119], v[186:189], v[36:39]
	v_mfma_f32_16x16x32_bf16 v[140:143], v[108:111], v[204:207], v[140:143]
	v_mfma_f32_16x16x32_bf16 v[56:59], v[116:119], v[204:207], v[56:59]
	v_mfma_f32_16x16x32_bf16 v[100:103], v[108:111], v[212:215], v[100:103]
	v_mfma_f32_16x16x32_bf16 v[48:51], v[116:119], v[212:215], v[48:51]
	s_setprio 0
	s_setprio 1
	v_mfma_f32_16x16x32_bf16 v[156:159], v[120:123], v[148:151], v[156:159]
	v_mfma_f32_16x16x32_bf16 v[52:55], v[128:131], v[148:151], v[52:55]
	v_mfma_f32_16x16x32_bf16 v[144:147], v[120:123], v[168:171], v[144:147]
	v_mfma_f32_16x16x32_bf16 v[32:35], v[128:131], v[168:171], v[32:35]
	v_mfma_f32_16x16x32_bf16 v[136:139], v[120:123], v[200:203], v[136:139]
	v_mfma_f32_16x16x32_bf16 v[44:47], v[128:131], v[200:203], v[44:47]
	v_mfma_f32_16x16x32_bf16 v[96:99], v[120:123], v[208:211], v[96:99]
	v_mfma_f32_16x16x32_bf16 v[40:43], v[128:131], v[208:211], v[40:43]
	v_mfma_f32_16x16x32_bf16 v[156:159], v[124:127], v[164:167], v[156:159]
	v_mfma_f32_16x16x32_bf16 v[52:55], v[132:135], v[164:167], v[52:55]
	v_mfma_f32_16x16x32_bf16 v[148:151], v[124:127], v[186:189], v[144:147]
	v_mfma_f32_16x16x32_bf16 v[32:35], v[132:135], v[186:189], v[32:35]
	v_mfma_f32_16x16x32_bf16 v[136:139], v[124:127], v[204:207], v[136:139]
	v_mfma_f32_16x16x32_bf16 v[44:47], v[132:135], v[204:207], v[44:47]
	v_mfma_f32_16x16x32_bf16 v[96:99], v[124:127], v[212:215], v[96:99]
	v_mfma_f32_16x16x32_bf16 v[40:43], v[132:135], v[212:215], v[40:43]
	s_setprio 0
	s_barrier
	global_load_lds_dwordx4 v192, s[100:101]
	s_add_i32 m0, s89, 0x1a000
	ds_read_b128 v[144:147], v231 offset:49152
	ds_read_b128 v[164:167], v231 offset:50176
	global_load_lds_dwordx4 v172, s[100:101]
	s_add_i32 m0, s89, 0x1c000
	ds_read_b128 v[168:171], v231 offset:51200
	ds_read_b128 v[186:189], v231 offset:52224
	global_load_lds_dwordx4 v192, s[62:63]
	s_add_i32 m0, s89, 0x1e000
	ds_read_b128 v[200:203], v231 offset:53248
	ds_read_b128 v[204:207], v231 offset:54272
	global_load_lds_dwordx4 v172, s[62:63]
	ds_read_b128 v[208:211], v231 offset:55296
	ds_read_b128 v[212:215], v231 offset:56320
	s_add_i32 s93, s93, 2
	s_add_u32 s54, s54, 0x100
	s_addc_u32 s55, s55, 0
	s_add_u32 s60, s60, 0x100
	s_addc_u32 s61, s61, 0
	s_add_u32 s56, s54, 0x100
	s_addc_u32 s57, s55, 0
	s_cmp_eq_u32 s93, 28
	s_cselect_b32 s49, s41, s57
	s_cselect_b32 s48, s42, s56
	s_cselect_b32 vcc_hi, s43, s61
	s_cselect_b32 vcc_lo, s59, s60
	s_mov_b32 m0, s94
	s_add_u32 s100, s54, 0x80
	s_addc_u32 s101, s55, 0
	s_cmp_gt_u32 s93, 29
	s_waitcnt vmcnt(6) lgkmcnt(0)
	s_barrier
	s_setprio 1
	v_mfma_f32_16x16x32_bf16 v[92:95], v[104:107], v[144:147], v[92:95]
	v_mfma_f32_16x16x32_bf16 v[28:31], v[112:115], v[144:147], v[28:31]
	v_mfma_f32_16x16x32_bf16 v[88:91], v[104:107], v[168:171], v[88:91]
	v_mfma_f32_16x16x32_bf16 v[4:7], v[112:115], v[168:171], v[4:7]
	v_mfma_f32_16x16x32_bf16 v[80:83], v[104:107], v[200:203], v[80:83]
	v_mfma_f32_16x16x32_bf16 v[24:27], v[112:115], v[200:203], v[24:27]
	v_mfma_f32_16x16x32_bf16 v[72:75], v[104:107], v[208:211], v[72:75]
	v_mfma_f32_16x16x32_bf16 v[16:19], v[112:115], v[208:211], v[16:19]
	v_mfma_f32_16x16x32_bf16 v[92:95], v[108:111], v[164:167], v[92:95]
	v_mfma_f32_16x16x32_bf16 v[28:31], v[116:119], v[164:167], v[28:31]
	v_mfma_f32_16x16x32_bf16 v[88:91], v[108:111], v[186:189], v[88:91]
	v_mfma_f32_16x16x32_bf16 v[4:7], v[116:119], v[186:189], v[4:7]
	v_mfma_f32_16x16x32_bf16 v[80:83], v[108:111], v[204:207], v[80:83]
	v_mfma_f32_16x16x32_bf16 v[24:27], v[116:119], v[204:207], v[24:27]
	v_mfma_f32_16x16x32_bf16 v[72:75], v[108:111], v[212:215], v[72:75]
	v_mfma_f32_16x16x32_bf16 v[16:19], v[116:119], v[212:215], v[16:19]
	s_setprio 0
	s_setprio 1
	v_mfma_f32_16x16x32_bf16 v[84:87], v[120:123], v[144:147], v[84:87]
	v_mfma_f32_16x16x32_bf16 v[20:23], v[128:131], v[144:147], v[20:23]
	v_mfma_f32_16x16x32_bf16 v[76:79], v[120:123], v[168:171], v[76:79]
	v_mfma_f32_16x16x32_bf16 v[0:3], v[128:131], v[168:171], v[0:3]
	v_mfma_f32_16x16x32_bf16 v[68:71], v[120:123], v[200:203], v[68:71]
	v_mfma_f32_16x16x32_bf16 v[12:15], v[128:131], v[200:203], v[12:15]
	v_mfma_f32_16x16x32_bf16 v[64:67], v[120:123], v[208:211], v[64:67]
	v_mfma_f32_16x16x32_bf16 v[8:11], v[128:131], v[208:211], v[8:11]
	v_mfma_f32_16x16x32_bf16 v[84:87], v[124:127], v[164:167], v[84:87]
	v_mfma_f32_16x16x32_bf16 v[20:23], v[132:135], v[164:167], v[20:23]
	v_mfma_f32_16x16x32_bf16 v[76:79], v[124:127], v[186:189], v[76:79]
	v_mfma_f32_16x16x32_bf16 v[0:3], v[132:135], v[186:189], v[0:3]
	v_mfma_f32_16x16x32_bf16 v[68:71], v[124:127], v[204:207], v[68:71]
	v_mfma_f32_16x16x32_bf16 v[12:15], v[132:135], v[204:207], v[12:15]
	v_mfma_f32_16x16x32_bf16 v[64:67], v[124:127], v[212:215], v[64:67]
	v_mfma_f32_16x16x32_bf16 v[8:11], v[132:135], v[212:215], v[8:11]
	s_setprio 0
	s_barrier
	s_cbranch_scc0 .LBB0_968
	s_and_b64 vcc, exec, s[82:83]
	s_cbranch_vccz .LBB0_971
	s_barrier
